# phase 2: per-channel mu_v / v0 via scalar loads one q ahead (removes 16-32 exposed L2 latencies per nt iteration)
# speedup vs baseline: 1.0155x; 1.0034x over previous
; #define MFMA32(a, b, c) __builtin_amdgcn_mfma_f32_32x32x16_bf16((a), (b), (c), 0, 0, 0)
; DI float bflo(unsigned u) { return __uint_as_float(u << 16); }
; DI float bfhi(unsigned u) { return __uint_as_float(u & 0xffff0000u); }
; DI float sigmoidf_(float x) { return __builtin_amdgcn_rcpf(1.f + __expf(-x)); }
; DI void rwkv_prep(const Params& p, int l, int item, char* smraw) {
;     ...
;     for (int nt = 0; nt < 2; ++nt) {
;       f32x16 aw, aa, av;
; #pragma unroll
;       for (int e = 0; e < 16; ++e) { aw[e] = 0.f; aa[e] = 0.f; av[e] = 0.f; }
; #pragma unroll
;       for (int s = 0; s < 4; ++s) {
;         const bf16x8 f1 = *(const bf16x8*)(A1 + (32 * tt + r31) * LDT + 16 * s + 8 * h);
;         const bf16x8 f2 = *(const bf16x8*)(A2 + (32 * tt + r31) * LDT + 16 * s + 8 * h);
;         const bf16x8 gw = *(const bf16x8*)(lw2 + (w * 64 + 32 * nt + r31) * 64 + 16 * s + 8 * h);
;         const bf16x8 ga = *(const bf16x8*)(la2 + (w * 64 + 32 * nt + r31) * 64 + 16 * s + 8 * h);
;         aw = MFMA32(gw, f1, aw);
;         aa = MFMA32(ga, f2, aa);
;       }
;       if (l == 1) {
;         f32x16 t1;
; #pragma unroll
;         for (int e = 0; e < 16; ++e) t1[e] = 0.f;
; #pragma unroll
;         for (int s = 0; s < 16; ++s) {
;           const bf16x8 fv = *(const bf16x8*)(A3 + (32 * tt + r31) * 264 + 16 * s + 8 * h);
;           const bf16x8 g1 = *(const bf16x8*)(v1t + r31 * 256 + 16 * s + 8 * h);
;     ...
;           xr = xr + (qr - xr) * mu[cc]; xk = xk + (qk - xk) * mu[256 + cc]; xv = xv + (qv - xv) * mu[512 + cc];
;           const float wl = w0[cc] + aw[i];
;           const float ew = 0.60653065971f * sigmoidf_(wl);
;           const float u = 1.f - __expf(-ew);
;           const float a = sigmoidf_(a0[cc] + aa[i]);
;           if (l == 1) {
;             const float vfirst = (e & 1) ? bfhi(vfu) : bflo(vfu);
;             xv = xv + (vfirst - xv) * sigmoidf_(v0[cc] + av[i]);
.LBB0_392:
	s_mov_b64 s[100:101], exec
	s_mov_b32 s98, 0
	s_mov_b32 s99, -1
	s_and_b64 s[98:99], s[100:101], s[98:99]
	v_readfirstlane_b32 s84, v120
	s_lshl_b32 s85, s4, 5
	s_add_i32 s85, s85, s84
	s_lshl_b32 s85, s85, 2
	s_add_i32 s86, s85, 0x800
	s_load_dwordx8 s[56:63], s[38:39], s86
	s_load_dwordx8 s[72:79], s[44:45], s85
	v_lshl_or_b32 v0, s4, 12, v97
	v_lshl_add_u64 v[50:51], v[88:89], 0, v[0:1]
	v_lshl_add_u64 v[52:53], v[90:91], 0, v[0:1]
	s_and_b64 vcc, exec, s[8:9]
	s_cbranch_vccz .Lp2_nog
	global_load_dwordx4 v[128:131], v[98:99], off
	global_load_dwordx4 v[132:135], v[98:99], off offset:32
	global_load_dwordx4 v[136:139], v[98:99], off offset:64
	global_load_dwordx4 v[140:143], v[98:99], off offset:96
	global_load_dwordx4 v[144:147], v[98:99], off offset:128
	global_load_dwordx4 v[148:151], v[98:99], off offset:160
	global_load_dwordx4 v[152:155], v[98:99], off offset:192
	global_load_dwordx4 v[156:159], v[98:99], off offset:224
	global_load_dwordx4 v[160:163], v[98:99], off offset:256
	global_load_dwordx4 v[164:167], v[98:99], off offset:288
	global_load_dwordx4 v[168:171], v[98:99], off offset:320
	global_load_dwordx4 v[172:175], v[98:99], off offset:352
	global_load_dwordx4 v[176:179], v[98:99], off offset:384
	global_load_dwordx4 v[180:183], v[98:99], off offset:416
	global_load_dwordx4 v[184:187], v[98:99], off offset:448
	global_load_dwordx4 v[188:191], v[98:99], off offset:480

; DI float bflo(unsigned u) { return __uint_as_float(u << 16); }
; DI float bfhi(unsigned u) { return __uint_as_float(u & 0xffff0000u); }
; DI float sigmoidf_(float x) { return __builtin_amdgcn_rcpf(1.f + __expf(-x)); }
; DI void rwkv_prep(const Params& p, int l, int item, char* smraw) {
;     ...
;       for (int q = 0; q < 4; ++q) {
;         const int cl = 32 * nt + 8 * q + 4 * h;
;         const int c = w * 64 + cl;
;         const uint2 zr = *(const uint2*)(SR + (tokl + 1) * 776 + c);
;         const uint2 zk = *(const uint2*)(SR + (tokl + 1) * 776 + 256 + c);
;         const uint2 zv = *(const uint2*)(SR + (tokl + 1) * 776 + 512 + c);
;         const uint2 pr_ = *(const uint2*)(SR + tokl * 776 + c);
;         const uint2 pk_ = *(const uint2*)(SR + tokl * 776 + 256 + c);
;         const uint2 pv_ = *(const uint2*)(SR + tokl * 776 + 512 + c);
;         uint2 vfl = make_uint2(0, 0);
;         if (l == 1) vfl = *(const uint2*)(vf + m * 256 + c);
;         float orr[4], ou[4], okp[4], ovv[4], oa[4], ob[4];
; #pragma unroll
;         for (int e = 0; e < 4; ++e) {
;           const int cc = c + e; const int i = 4 * q + e;
;           const unsigned zru = (e < 2) ? zr.x : zr.y, zku = (e < 2) ? zk.x : zk.y, zvu = (e < 2) ? zv.x : zv.y;
;           const unsigned pru = (e < 2) ? pr_.x : pr_.y, pku = (e < 2) ? pk_.x : pk_.y, pvu = (e < 2) ? pv_.x : pv_.y;
;           const unsigned vfu = (e < 2) ? vfl.x : vfl.y;
;           float xr = (e & 1) ? bfhi(zru) : bflo(zru), xk = (e & 1) ? bfhi(zku) : bflo(zku), xv = (e & 1) ? bfhi(zvu) : bflo(zvu);
;           const float qr = (e & 1) ? bfhi(pru) : bflo(pru), qk = (e & 1) ? bfhi(pku) : bflo(pku), qv = (e & 1) ? bfhi(pvu) : bflo(pvu);
;           xr = xr + (qr - xr) * mu[cc]; xk = xk + (qk - xk) * mu[256 + cc]; xv = xv + (qv - xv) * mu[512 + cc];
;           const float wl = w0[cc] + aw[i];
;           const float ew = 0.60653065971f * sigmoidf_(wl);
;           const float u = 1.f - __expf(-ew);
;           const float a = sigmoidf_(a0[cc] + aa[i]);
;           if (l == 1) {
;             const float vfirst = (e & 1) ? bfhi(vfu) : bflo(vfu);
;             xv = xv + (vfirst - xv) * sigmoidf_(v0[cc] + av[i]);
.LBB0_396:
	v_lshlrev_b64 v[64:65], 2, v[0:1]
	v_lshl_add_u64 v[108:109], s[38:39], 0, v[64:65]
	global_load_dword v144, v[108:109], off
	global_load_dword v143, v[108:109], off offset:1024
	v_lshl_add_u64 v[110:111], s[46:47], 0, v[64:65]
	v_lshl_add_u64 v[112:113], s[48:49], 0, v[64:65]
	global_load_dword v131, v[110:111], off
	global_load_dword v150, v[112:113], off
	s_waitcnt lgkmcnt(1)
	v_lshlrev_b32_e32 v130, 16, v56
	v_lshlrev_b32_e32 v66, 16, v50
	v_sub_f32_e32 v66, v66, v130
	s_and_b64 vcc, exec, s[36:37]
	v_lshl_add_u64 v[114:115], v[0:1], 2, s[44:45]
	s_waitcnt lgkmcnt(0)
	s_add_i32 s85, s85, 32
	s_add_i32 s86, s86, 32
	s_load_dwordx8 s[88:95], s[38:39], s86
	s_load_dwordx4 s[64:67], s[44:45], s85
	s_add_i32 s96, s85, 16
	s_load_dwordx4 s[80:83], s[44:45], s96
	v_mov_b32_e32 v67, s56
	s_mov_b64 exec, s[98:99]
	v_mov_b32_e32 v67, s60
	s_mov_b64 exec, s[100:101]
	v_fmac_f32_e32 v130, v66, v67
	s_cbranch_vccnz .LBB0_398
	v_mov_b32_e32 v0, s72
	s_mov_b64 exec, s[98:99]
	v_mov_b32_e32 v0, s76
	s_mov_b64 exec, s[100:101]
	s_waitcnt vmcnt(4)
	v_add_f32_e32 v0, v34, v0
	v_mul_f32_e32 v0, 0xbfb8aa3b, v0
	v_exp_f32_e32 v0, v0
	v_lshlrev_b32_e32 v34, 16, v62
	v_sub_f32_e32 v34, v34, v130
	v_add_f32_e32 v0, 1.0, v0
	v_rcp_f32_e32 v0, v0
	s_nop 0
	v_fmac_f32_e32 v130, v34, v0
.LBB0_398:
	v_lshl_add_u64 v[102:103], s[40:41], 0, v[64:65]
	v_lshl_add_u64 v[104:105], s[50:51], 0, v[64:65]
	v_lshl_add_u64 v[106:107], s[52:53], 0, v[64:65]
	global_load_dword v134, v[102:103], off
	global_load_dword v158, v[104:105], off
	global_load_dword v125, v[106:107], off
	v_and_b32_e32 v34, 0xffff0000, v50
	global_load_dword v157, v[108:109], off offset:4
	global_load_dword v155, v[108:109], off offset:1028
	global_load_dword v135, v[110:111], off offset:4
	global_load_dword v161, v[112:113], off offset:4
	v_and_b32_e32 v0, 0xffff0000, v56
	v_sub_f32_e32 v34, v34, v0
	s_and_b64 vcc, exec, s[36:37]
	v_mov_b32_e32 v50, s57
	s_mov_b64 exec, s[98:99]
	v_mov_b32_e32 v50, s61
	s_mov_b64 exec, s[100:101]
	v_fmac_f32_e32 v0, v34, v50
	s_cbranch_vccnz .LBB0_400
	v_mov_b32_e32 v34, s73
	s_mov_b64 exec, s[98:99]
	v_mov_b32_e32 v34, s77
	s_mov_b64 exec, s[100:101]
	v_add_f32_e32 v34, v35, v34
	v_mul_f32_e32 v34, 0xbfb8aa3b, v34
	v_exp_f32_e32 v34, v34
	v_and_b32_e32 v35, 0xffff0000, v62
	v_sub_f32_e32 v35, v35, v0
	v_add_f32_e32 v34, 1.0, v34
	v_rcp_f32_e32 v34, v34
	s_nop 0
	v_fmac_f32_e32 v0, v35, v34
.LBB0_400:
	global_load_dword v140, v[102:103], off offset:4
	global_load_dword v172, v[104:105], off offset:4
	global_load_dword v56, v[106:107], off offset:4
	global_load_dword v171, v[108:109], off offset:8
	global_load_dword v170, v[108:109], off offset:1032
	global_load_dword v145, v[110:111], off offset:8
	global_load_dword v175, v[112:113], off offset:8
	v_lshlrev_b32_e32 v137, 16, v57
	v_lshlrev_b32_e32 v34, 16, v51
	v_sub_f32_e32 v34, v34, v137
	s_and_b64 vcc, exec, s[36:37]
	v_mov_b32_e32 v35, s58
	s_mov_b64 exec, s[98:99]
	v_mov_b32_e32 v35, s62
	s_mov_b64 exec, s[100:101]
	v_fmac_f32_e32 v137, v34, v35
	s_cbranch_vccnz .LBB0_402
	v_mov_b32_e32 v34, s74
	s_mov_b64 exec, s[98:99]
	v_mov_b32_e32 v34, s78
	s_mov_b64 exec, s[100:101]
	v_lshlrev_b32_e32 v35, 16, v63
	v_sub_f32_e32 v35, v35, v137
	v_add_f32_e32 v34, v36, v34
	v_mul_f32_e32 v34, 0xbfb8aa3b, v34
	v_exp_f32_e32 v34, v34
	s_nop 0
	v_add_f32_e32 v34, 1.0, v34
	v_rcp_f32_e32 v34, v34
	s_nop 0
	v_fmac_f32_e32 v137, v35, v34
.LBB0_402:
	global_load_dword v153, v[102:103], off offset:8
	global_load_dword v186, v[104:105], off offset:8
	global_load_dword v126, v[106:107], off offset:8
	global_load_dword v184, v[108:109], off offset:12
	global_load_dword v183, v[108:109], off offset:1036
	global_load_dword v163, v[110:111], off offset:12
	global_load_dword v191, v[112:113], off offset:12
	v_and_b32_e32 v142, 0xffff0000, v57
	v_and_b32_e32 v34, 0xffff0000, v51
	v_sub_f32_e32 v34, v34, v142
	s_and_b64 vcc, exec, s[36:37]
	v_mov_b32_e32 v35, s59
	s_mov_b64 exec, s[98:99]
	v_mov_b32_e32 v35, s63
	s_mov_b64 exec, s[100:101]
	v_fmac_f32_e32 v142, v34, v35
	s_cbranch_vccnz .LBB0_404
	v_mov_b32_e32 v34, s75
	s_mov_b64 exec, s[98:99]
	v_mov_b32_e32 v34, s79
	s_mov_b64 exec, s[100:101]
	v_and_b32_e32 v35, 0xffff0000, v63
	v_sub_f32_e32 v35, v35, v142
	v_add_f32_e32 v34, v37, v34
	v_mul_f32_e32 v34, 0xbfb8aa3b, v34
	v_exp_f32_e32 v34, v34
	s_nop 0
	v_add_f32_e32 v34, 1.0, v34
	v_rcp_f32_e32 v34, v34
	s_nop 0
	v_fmac_f32_e32 v142, v35, v34

; DI float bflo(unsigned u) { return __uint_as_float(u << 16); }
; DI float bfhi(unsigned u) { return __uint_as_float(u & 0xffff0000u); }
; DI float sigmoidf_(float x) { return __builtin_amdgcn_rcpf(1.f + __expf(-x)); }
; DI void rwkv_prep(const Params& p, int l, int item, char* smraw) {
;     ...
;       for (int q = 0; q < 4; ++q) {
;         const int cl = 32 * nt + 8 * q + 4 * h;
;         const int c = w * 64 + cl;
;         const uint2 zr = *(const uint2*)(SR + (tokl + 1) * 776 + c);
;         const uint2 zk = *(const uint2*)(SR + (tokl + 1) * 776 + 256 + c);
;         const uint2 zv = *(const uint2*)(SR + (tokl + 1) * 776 + 512 + c);
;         const uint2 pr_ = *(const uint2*)(SR + tokl * 776 + c);
;         const uint2 pk_ = *(const uint2*)(SR + tokl * 776 + 256 + c);
;         const uint2 pv_ = *(const uint2*)(SR + tokl * 776 + 512 + c);
;         uint2 vfl = make_uint2(0, 0);
;         if (l == 1) vfl = *(const uint2*)(vf + m * 256 + c);
;         float orr[4], ou[4], okp[4], ovv[4], oa[4], ob[4];
; #pragma unroll
;         for (int e = 0; e < 4; ++e) {
;           const int cc = c + e; const int i = 4 * q + e;
;           const unsigned zru = (e < 2) ? zr.x : zr.y, zku = (e < 2) ? zk.x : zk.y, zvu = (e < 2) ? zv.x : zv.y;
;           const unsigned pru = (e < 2) ? pr_.x : pr_.y, pku = (e < 2) ? pk_.x : pk_.y, pvu = (e < 2) ? pv_.x : pv_.y;
;           const unsigned vfu = (e < 2) ? vfl.x : vfl.y;
;           float xr = (e & 1) ? bfhi(zru) : bflo(zru), xk = (e & 1) ? bfhi(zku) : bflo(zku), xv = (e & 1) ? bfhi(zvu) : bflo(zvu);
;           const float qr = (e & 1) ? bfhi(pru) : bflo(pru), qk = (e & 1) ? bfhi(pku) : bflo(pku), qv = (e & 1) ? bfhi(pvu) : bflo(pvu);
;           xr = xr + (qr - xr) * mu[cc]; xk = xk + (qk - xk) * mu[256 + cc]; xv = xv + (qv - xv) * mu[512 + cc];
;           const float wl = w0[cc] + aw[i];
;           const float ew = 0.60653065971f * sigmoidf_(wl);
;           const float u = 1.f - __expf(-ew);
;           const float a = sigmoidf_(a0[cc] + aa[i]);
;           if (l == 1) {
;             const float vfirst = (e & 1) ? bfhi(vfu) : bflo(vfu);
;             xv = xv + (vfirst - xv) * sigmoidf_(v0[cc] + av[i]);
.LBB0_406:
	s_nop 0
	global_load_dword v152, v[108:109], off offset:32
	global_load_dword v151, v[108:109], off offset:1056
	global_load_dword v136, v[110:111], off offset:32
	global_load_dword v159, v[112:113], off offset:32
	s_waitcnt lgkmcnt(1)
	v_lshlrev_b32_e32 v132, 16, v68
	v_lshlrev_b32_e32 v70, 16, v62
	v_sub_f32_e32 v70, v70, v132
	s_and_b64 vcc, exec, s[36:37]
	s_waitcnt lgkmcnt(0)
	s_add_i32 s85, s85, 32
	s_add_i32 s86, s86, 32
	s_load_dwordx8 s[56:63], s[38:39], s86
	s_load_dwordx8 s[72:79], s[44:45], s85
	v_mov_b32_e32 v71, s88
	s_mov_b64 exec, s[98:99]
	v_mov_b32_e32 v71, s92
	s_mov_b64 exec, s[100:101]
	v_fmac_f32_e32 v132, v70, v71
	s_cbranch_vccnz .LBB0_408
	v_mov_b32_e32 v70, s64
	s_mov_b64 exec, s[98:99]
	v_mov_b32_e32 v70, s80
	s_mov_b64 exec, s[100:101]
	s_waitcnt vmcnt(4)
	v_add_f32_e32 v38, v38, v70
	v_mul_f32_e32 v38, 0xbfb8aa3b, v38
	v_exp_f32_e32 v38, v38
	v_lshlrev_b32_e32 v70, 16, v50
	v_sub_f32_e32 v70, v70, v132
	v_add_f32_e32 v38, 1.0, v38
	v_rcp_f32_e32 v38, v38
	s_nop 0
	v_fmac_f32_e32 v132, v70, v38
.LBB0_408:
	global_load_dword v141, v[102:103], off offset:32
	global_load_dword v167, v[104:105], off offset:32
	global_load_dword v127, v[106:107], off offset:32
	v_and_b32_e32 v38, 0xffff0000, v62
	global_load_dword v165, v[108:109], off offset:36
	global_load_dword v164, v[108:109], off offset:1060
	global_load_dword v146, v[110:111], off offset:36
	global_load_dword v173, v[112:113], off offset:36
	v_and_b32_e32 v138, 0xffff0000, v68
	v_sub_f32_e32 v38, v38, v138
	s_and_b64 vcc, exec, s[36:37]
	v_mov_b32_e32 v62, s89
	s_mov_b64 exec, s[98:99]
	v_mov_b32_e32 v62, s93
	s_mov_b64 exec, s[100:101]
	v_fmac_f32_e32 v138, v38, v62
	s_cbranch_vccnz .LBB0_410
	v_mov_b32_e32 v38, s65
	s_mov_b64 exec, s[98:99]
	v_mov_b32_e32 v38, s81
	s_mov_b64 exec, s[100:101]
	v_add_f32_e32 v38, v39, v38
	v_mul_f32_e32 v38, 0xbfb8aa3b, v38
	v_exp_f32_e32 v38, v38
	v_and_b32_e32 v39, 0xffff0000, v50
	v_sub_f32_e32 v39, v39, v138
	v_add_f32_e32 v38, 1.0, v38
	v_rcp_f32_e32 v38, v38
	s_nop 0
	v_fmac_f32_e32 v138, v39, v38
.LBB0_410:
	global_load_dword v156, v[102:103], off offset:36
	global_load_dword v180, v[104:105], off offset:36
	global_load_dword v62, v[106:107], off offset:36
	global_load_dword v179, v[108:109], off offset:40
	global_load_dword v177, v[108:109], off offset:1064
	global_load_dword v168, v[110:111], off offset:40
	global_load_dword v188, v[112:113], off offset:40
	v_lshlrev_b32_e32 v147, 16, v69
	v_lshlrev_b32_e32 v38, 16, v63
	v_sub_f32_e32 v38, v38, v147
	s_and_b64 vcc, exec, s[36:37]
	v_mov_b32_e32 v39, s90
	s_mov_b64 exec, s[98:99]
	v_mov_b32_e32 v39, s94
	s_mov_b64 exec, s[100:101]
	v_fmac_f32_e32 v147, v38, v39
	s_cbranch_vccnz .LBB0_412
	v_mov_b32_e32 v38, s66
	s_mov_b64 exec, s[98:99]
	v_mov_b32_e32 v38, s82
	s_mov_b64 exec, s[100:101]
	v_lshlrev_b32_e32 v39, 16, v51
	v_sub_f32_e32 v39, v39, v147
	v_add_f32_e32 v38, v40, v38
	v_mul_f32_e32 v38, 0xbfb8aa3b, v38
	v_exp_f32_e32 v38, v38
	s_nop 0
	v_add_f32_e32 v38, 1.0, v38
	v_rcp_f32_e32 v38, v38
	s_nop 0
	v_fmac_f32_e32 v147, v39, v38
.LBB0_412:
	global_load_dword v185, v[102:103], off offset:40
	global_load_dword v199, v[104:105], off offset:40
	global_load_dword v128, v[106:107], off offset:40
	global_load_dword v195, v[108:109], off offset:44
	global_load_dword v193, v[108:109], off offset:1068
	global_load_dword v196, v[110:111], off offset:44
	global_load_dword v211, v[112:113], off offset:44
	v_and_b32_e32 v162, 0xffff0000, v69
	v_and_b32_e32 v38, 0xffff0000, v63
	v_sub_f32_e32 v38, v38, v162
	s_and_b64 vcc, exec, s[36:37]
	v_mov_b32_e32 v39, s91
	s_mov_b64 exec, s[98:99]
	v_mov_b32_e32 v39, s95
	s_mov_b64 exec, s[100:101]
	v_fmac_f32_e32 v162, v38, v39
	s_cbranch_vccnz .LBB0_414
	v_mov_b32_e32 v38, s67
	s_mov_b64 exec, s[98:99]
	v_mov_b32_e32 v38, s83
	s_mov_b64 exec, s[100:101]
	v_and_b32_e32 v39, 0xffff0000, v51
	v_sub_f32_e32 v39, v39, v162
	v_add_f32_e32 v38, v41, v38
	v_mul_f32_e32 v38, 0xbfb8aa3b, v38
	v_exp_f32_e32 v38, v38
	s_nop 0
	v_add_f32_e32 v38, 1.0, v38
	v_rcp_f32_e32 v38, v38
	s_nop 0
	v_fmac_f32_e32 v162, v39, v38

; DI float bflo(unsigned u) { return __uint_as_float(u << 16); }
; DI float bfhi(unsigned u) { return __uint_as_float(u & 0xffff0000u); }
; DI float sigmoidf_(float x) { return __builtin_amdgcn_rcpf(1.f + __expf(-x)); }
; DI void rwkv_prep(const Params& p, int l, int item, char* smraw) {
;     ...
;       for (int q = 0; q < 4; ++q) {
;         const int cl = 32 * nt + 8 * q + 4 * h;
;         const int c = w * 64 + cl;
;         const uint2 zr = *(const uint2*)(SR + (tokl + 1) * 776 + c);
;         const uint2 zk = *(const uint2*)(SR + (tokl + 1) * 776 + 256 + c);
;         const uint2 zv = *(const uint2*)(SR + (tokl + 1) * 776 + 512 + c);
;         const uint2 pr_ = *(const uint2*)(SR + tokl * 776 + c);
;         const uint2 pk_ = *(const uint2*)(SR + tokl * 776 + 256 + c);
;         const uint2 pv_ = *(const uint2*)(SR + tokl * 776 + 512 + c);
;         uint2 vfl = make_uint2(0, 0);
;         if (l == 1) vfl = *(const uint2*)(vf + m * 256 + c);
;         float orr[4], ou[4], okp[4], ovv[4], oa[4], ob[4];
; #pragma unroll
;         for (int e = 0; e < 4; ++e) {
;           const int cc = c + e; const int i = 4 * q + e;
;           const unsigned zru = (e < 2) ? zr.x : zr.y, zku = (e < 2) ? zk.x : zk.y, zvu = (e < 2) ? zv.x : zv.y;
;           const unsigned pru = (e < 2) ? pr_.x : pr_.y, pku = (e < 2) ? pk_.x : pk_.y, pvu = (e < 2) ? pv_.x : pv_.y;
;           const unsigned vfu = (e < 2) ? vfl.x : vfl.y;
;           float xr = (e & 1) ? bfhi(zru) : bflo(zru), xk = (e & 1) ? bfhi(zku) : bflo(zku), xv = (e & 1) ? bfhi(zvu) : bflo(zvu);
;           const float qr = (e & 1) ? bfhi(pru) : bflo(pru), qk = (e & 1) ? bfhi(pku) : bflo(pku), qv = (e & 1) ? bfhi(pvu) : bflo(pvu);
;           xr = xr + (qr - xr) * mu[cc]; xk = xk + (qk - xk) * mu[256 + cc]; xv = xv + (qv - xv) * mu[512 + cc];
;           const float wl = w0[cc] + aw[i];
;           const float ew = 0.60653065971f * sigmoidf_(wl);
;           const float u = 1.f - __expf(-ew);
;           const float a = sigmoidf_(a0[cc] + aa[i]);
;           if (l == 1) {
;             const float vfirst = (e & 1) ? bfhi(vfu) : bflo(vfu);
;             xv = xv + (vfirst - xv) * sigmoidf_(v0[cc] + av[i]);
.LBB0_416:
	s_nop 0
	global_load_dword v178, v[108:109], off offset:64
	global_load_dword v176, v[108:109], off offset:1088
	global_load_dword v148, v[110:111], off offset:64
	global_load_dword v187, v[112:113], off offset:64
	s_waitcnt lgkmcnt(1)
	v_lshlrev_b32_e32 v139, 16, v74
	v_lshlrev_b32_e32 v77, 16, v68
	v_sub_f32_e32 v77, v77, v139
	s_and_b64 vcc, exec, s[36:37]
	s_waitcnt lgkmcnt(0)
	s_add_i32 s85, s85, 32
	s_add_i32 s86, s86, 32
	s_load_dwordx8 s[88:95], s[38:39], s86
	s_load_dwordx4 s[64:67], s[44:45], s85
	s_add_i32 s96, s85, 16
	s_load_dwordx4 s[80:83], s[44:45], s96
	v_mov_b32_e32 v79, s56
	s_mov_b64 exec, s[98:99]
	v_mov_b32_e32 v79, s60
	s_mov_b64 exec, s[100:101]
	v_fmac_f32_e32 v139, v77, v79
	s_cbranch_vccnz .LBB0_418
	v_mov_b32_e32 v77, s72
	s_mov_b64 exec, s[98:99]
	v_mov_b32_e32 v77, s76
	s_mov_b64 exec, s[100:101]
	s_waitcnt vmcnt(4)
	v_add_f32_e32 v42, v42, v77
	v_mul_f32_e32 v42, 0xbfb8aa3b, v42
	v_exp_f32_e32 v42, v42
	v_lshlrev_b32_e32 v77, 16, v50
	v_sub_f32_e32 v77, v77, v139
	v_add_f32_e32 v42, 1.0, v42
	v_rcp_f32_e32 v42, v42
	s_nop 0
	v_fmac_f32_e32 v139, v77, v42
.LBB0_418:
	global_load_dword v154, v[102:103], off offset:64
	global_load_dword v197, v[104:105], off offset:64
	global_load_dword v129, v[106:107], off offset:64
	v_and_b32_e32 v42, 0xffff0000, v68
	global_load_dword v194, v[108:109], off offset:68
	global_load_dword v192, v[108:109], off offset:1092
	global_load_dword v166, v[110:111], off offset:68
	global_load_dword v210, v[112:113], off offset:68
	v_and_b32_e32 v149, 0xffff0000, v74
	v_sub_f32_e32 v42, v42, v149
	s_and_b64 vcc, exec, s[36:37]
	v_mov_b32_e32 v68, s57
	s_mov_b64 exec, s[98:99]
	v_mov_b32_e32 v68, s61
	s_mov_b64 exec, s[100:101]
	v_fmac_f32_e32 v149, v42, v68
	s_cbranch_vccnz .LBB0_420
	v_mov_b32_e32 v42, s73
	s_mov_b64 exec, s[98:99]
	v_mov_b32_e32 v42, s77
	s_mov_b64 exec, s[100:101]
	v_add_f32_e32 v42, v43, v42
	v_mul_f32_e32 v42, 0xbfb8aa3b, v42
	v_exp_f32_e32 v42, v42
	v_and_b32_e32 v43, 0xffff0000, v50
	v_sub_f32_e32 v43, v43, v149
	v_add_f32_e32 v42, 1.0, v42
	v_rcp_f32_e32 v42, v42
	s_nop 0
	v_fmac_f32_e32 v149, v43, v42
.LBB0_420:
	global_load_dword v181, v[102:103], off offset:68
	global_load_dword v217, v[104:105], off offset:68
	global_load_dword v68, v[106:107], off offset:68
	global_load_dword v215, v[108:109], off offset:72
	global_load_dword v213, v[108:109], off offset:1096
	global_load_dword v198, v[110:111], off offset:72
	global_load_dword v221, v[112:113], off offset:72
	v_lshlrev_b32_e32 v169, 16, v75
	v_lshlrev_b32_e32 v42, 16, v69
	v_sub_f32_e32 v42, v42, v169
	s_and_b64 vcc, exec, s[36:37]
	v_mov_b32_e32 v43, s58
	s_mov_b64 exec, s[98:99]
	v_mov_b32_e32 v43, s62
	s_mov_b64 exec, s[100:101]
	v_fmac_f32_e32 v169, v42, v43
	s_cbranch_vccnz .LBB0_422
	v_mov_b32_e32 v42, s74
	s_mov_b64 exec, s[98:99]
	v_mov_b32_e32 v42, s78
	s_mov_b64 exec, s[100:101]
	v_lshlrev_b32_e32 v43, 16, v51
	v_sub_f32_e32 v43, v43, v169
	v_add_f32_e32 v42, v44, v42
	v_mul_f32_e32 v42, 0xbfb8aa3b, v42
	v_exp_f32_e32 v42, v42
	s_nop 0
	v_add_f32_e32 v42, 1.0, v42
	v_rcp_f32_e32 v42, v42
	s_nop 0
	v_fmac_f32_e32 v169, v43, v42
.LBB0_422:
	global_load_dword v218, v[102:103], off offset:72
	global_load_dword v237, v[104:105], off offset:72
	global_load_dword v133, v[106:107], off offset:72
	global_load_dword v234, v[108:109], off offset:76
	global_load_dword v232, v[108:109], off offset:1100
	global_load_dword v235, v[110:111], off offset:76
	global_load_dword v240, v[112:113], off offset:76
	v_and_b32_e32 v190, 0xffff0000, v75
	v_and_b32_e32 v42, 0xffff0000, v69
	v_sub_f32_e32 v42, v42, v190
	s_and_b64 vcc, exec, s[36:37]
	v_mov_b32_e32 v43, s59
	s_mov_b64 exec, s[98:99]
	v_mov_b32_e32 v43, s63
	s_mov_b64 exec, s[100:101]
	v_fmac_f32_e32 v190, v42, v43
	s_cbranch_vccnz .LBB0_424
	v_mov_b32_e32 v42, s75
	s_mov_b64 exec, s[98:99]
	v_mov_b32_e32 v42, s79
	s_mov_b64 exec, s[100:101]
	v_and_b32_e32 v43, 0xffff0000, v51
	v_sub_f32_e32 v43, v43, v190
	v_add_f32_e32 v42, v45, v42
	v_mul_f32_e32 v42, 0xbfb8aa3b, v42
	v_exp_f32_e32 v42, v42
	s_nop 0
	v_add_f32_e32 v42, 1.0, v42
	v_rcp_f32_e32 v42, v42
	s_nop 0
	v_fmac_f32_e32 v190, v43, v42

; DI float bflo(unsigned u) { return __uint_as_float(u << 16); }
; DI float bfhi(unsigned u) { return __uint_as_float(u & 0xffff0000u); }
; DI float sigmoidf_(float x) { return __builtin_amdgcn_rcpf(1.f + __expf(-x)); }
; DI void rwkv_prep(const Params& p, int l, int item, char* smraw) {
;     ...
;       for (int q = 0; q < 4; ++q) {
;         const int cl = 32 * nt + 8 * q + 4 * h;
;         const int c = w * 64 + cl;
;         const uint2 zr = *(const uint2*)(SR + (tokl + 1) * 776 + c);
;         const uint2 zk = *(const uint2*)(SR + (tokl + 1) * 776 + 256 + c);
;         const uint2 zv = *(const uint2*)(SR + (tokl + 1) * 776 + 512 + c);
;         const uint2 pr_ = *(const uint2*)(SR + tokl * 776 + c);
;         const uint2 pk_ = *(const uint2*)(SR + tokl * 776 + 256 + c);
;         const uint2 pv_ = *(const uint2*)(SR + tokl * 776 + 512 + c);
;         uint2 vfl = make_uint2(0, 0);
;         if (l == 1) vfl = *(const uint2*)(vf + m * 256 + c);
;         float orr[4], ou[4], okp[4], ovv[4], oa[4], ob[4];
; #pragma unroll
;         for (int e = 0; e < 4; ++e) {
;           const int cc = c + e; const int i = 4 * q + e;
;           const unsigned zru = (e < 2) ? zr.x : zr.y, zku = (e < 2) ? zk.x : zk.y, zvu = (e < 2) ? zv.x : zv.y;
;           const unsigned pru = (e < 2) ? pr_.x : pr_.y, pku = (e < 2) ? pk_.x : pk_.y, pvu = (e < 2) ? pv_.x : pv_.y;
;           const unsigned vfu = (e < 2) ? vfl.x : vfl.y;
;           float xr = (e & 1) ? bfhi(zru) : bflo(zru), xk = (e & 1) ? bfhi(zku) : bflo(zku), xv = (e & 1) ? bfhi(zvu) : bflo(zvu);
;           const float qr = (e & 1) ? bfhi(pru) : bflo(pru), qk = (e & 1) ? bfhi(pku) : bflo(pku), qv = (e & 1) ? bfhi(pvu) : bflo(pvu);
;           xr = xr + (qr - xr) * mu[cc]; xk = xk + (qk - xk) * mu[256 + cc]; xv = xv + (qv - xv) * mu[512 + cc];
;           const float wl = w0[cc] + aw[i];
;           const float ew = 0.60653065971f * sigmoidf_(wl);
;           const float u = 1.f - __expf(-ew);
;           const float a = sigmoidf_(a0[cc] + aa[i]);
;           if (l == 1) {
;             const float vfirst = (e & 1) ? bfhi(vfu) : bflo(vfu);
;             xv = xv + (vfirst - xv) * sigmoidf_(v0[cc] + av[i]);
.LBB0_426:
	s_nop 0
	global_load_dword v214, v[108:109], off offset:96
	global_load_dword v212, v[108:109], off offset:1120
	s_waitcnt lgkmcnt(1)
	v_lshlrev_b32_e32 v116, 16, v80
	v_lshlrev_b32_e32 v117, 16, v74
	v_sub_f32_e32 v117, v117, v116
	s_and_b64 vcc, exec, s[36:37]
	s_waitcnt lgkmcnt(0)
	v_mov_b32_e32 v182, s88
	s_mov_b64 exec, s[98:99]
	v_mov_b32_e32 v182, s92
	s_mov_b64 exec, s[100:101]
	v_fmac_f32_e32 v116, v117, v182
	global_load_dword v117, v[110:111], off offset:96
	global_load_dword v220, v[112:113], off offset:96
	s_cbranch_vccnz .LBB0_428
	v_mov_b32_e32 v182, s64
	s_mov_b64 exec, s[98:99]
	v_mov_b32_e32 v182, s80
	s_mov_b64 exec, s[100:101]
	s_waitcnt vmcnt(4)
	v_add_f32_e32 v46, v46, v182
	v_mul_f32_e32 v46, 0xbfb8aa3b, v46
	v_exp_f32_e32 v46, v46
	v_lshlrev_b32_e32 v182, 16, v50
	v_sub_f32_e32 v182, v182, v116
	v_add_f32_e32 v46, 1.0, v46
	v_rcp_f32_e32 v46, v46
	s_nop 0
	v_fmac_f32_e32 v116, v182, v46
.LBB0_428:
	global_load_dword v182, v[102:103], off offset:96
	global_load_dword v236, v[104:105], off offset:96
	global_load_dword v46, v[106:107], off offset:96
	global_load_dword v233, v[108:109], off offset:100
	global_load_dword v231, v[108:109], off offset:1124
	v_and_b32_e32 v80, 0xffff0000, v80
	v_and_b32_e32 v74, 0xffff0000, v74
	v_sub_f32_e32 v74, v74, v80
	s_and_b64 vcc, exec, s[36:37]
	v_mov_b32_e32 v219, s89
	s_mov_b64 exec, s[98:99]
	v_mov_b32_e32 v219, s93
	s_mov_b64 exec, s[100:101]
	v_fmac_f32_e32 v80, v74, v219
	global_load_dword v74, v[110:111], off offset:100
	global_load_dword v239, v[112:113], off offset:100
	s_cbranch_vccnz .LBB0_430
	v_mov_b32_e32 v219, s65
	s_mov_b64 exec, s[98:99]
	v_mov_b32_e32 v219, s81
	s_mov_b64 exec, s[100:101]
	v_and_b32_e32 v50, 0xffff0000, v50
	v_sub_f32_e32 v50, v50, v80
	v_add_f32_e32 v47, v47, v219
	v_mul_f32_e32 v47, 0xbfb8aa3b, v47
	v_exp_f32_e32 v47, v47
	s_nop 0
	v_add_f32_e32 v47, 1.0, v47
	v_rcp_f32_e32 v47, v47
	s_nop 0
	v_fmac_f32_e32 v80, v50, v47
.LBB0_430:
	global_load_dword v219, v[102:103], off offset:100
	global_load_dword v244, v[104:105], off offset:100
	global_load_dword v47, v[106:107], off offset:100
	global_load_dword v243, v[108:109], off offset:104
	global_load_dword v242, v[108:109], off offset:1128
	v_lshlrev_b32_e32 v50, 16, v81
	v_lshlrev_b32_e32 v238, 16, v75
	v_sub_f32_e32 v238, v238, v50
	s_and_b64 vcc, exec, s[36:37]
	v_mov_b32_e32 v245, s90
	s_mov_b64 exec, s[98:99]
	v_mov_b32_e32 v245, s94
	s_mov_b64 exec, s[100:101]
	v_fmac_f32_e32 v50, v238, v245
	global_load_dword v238, v[110:111], off offset:104
	global_load_dword v245, v[112:113], off offset:104
	s_cbranch_vccnz .LBB0_432
	v_mov_b32_e32 v246, s66
	s_mov_b64 exec, s[98:99]
	v_mov_b32_e32 v246, s82
	s_mov_b64 exec, s[100:101]
	v_add_f32_e32 v48, v48, v246
	v_mul_f32_e32 v48, 0xbfb8aa3b, v48
	v_exp_f32_e32 v48, v48
	v_lshlrev_b32_e32 v246, 16, v51
	v_sub_f32_e32 v246, v246, v50
	v_add_f32_e32 v48, 1.0, v48
	v_rcp_f32_e32 v48, v48
	s_nop 0
	v_fmac_f32_e32 v50, v246, v48
.LBB0_432:
	global_load_dword v249, v[102:103], off offset:104
	global_load_dword v248, v[104:105], off offset:104
	global_load_dword v48, v[106:107], off offset:104
	global_load_dword v247, v[108:109], off offset:108
	global_load_dword v246, v[108:109], off offset:1132
	s_nop 0
	global_load_dword v109, v[110:111], off offset:108
	global_load_dword v108, v[112:113], off offset:108
	v_and_b32_e32 v81, 0xffff0000, v81
	v_and_b32_e32 v75, 0xffff0000, v75
	v_sub_f32_e32 v75, v75, v81
	s_and_b64 vcc, exec, s[36:37]
	s_waitcnt vmcnt(2)
	v_mov_b32_e32 v250, s91
	s_mov_b64 exec, s[98:99]
	v_mov_b32_e32 v250, s95
	s_mov_b64 exec, s[100:101]
	v_fmac_f32_e32 v81, v75, v250
	s_cbranch_vccnz .LBB0_434
	v_mov_b32_e32 v75, s67
	s_mov_b64 exec, s[98:99]
	v_mov_b32_e32 v75, s83
	s_mov_b64 exec, s[100:101]
	v_and_b32_e32 v51, 0xffff0000, v51
	v_sub_f32_e32 v51, v51, v81
	v_add_f32_e32 v49, v49, v75
	v_mul_f32_e32 v49, 0xbfb8aa3b, v49
	v_exp_f32_e32 v49, v49
	s_nop 0
	v_add_f32_e32 v49, 1.0, v49
	v_rcp_f32_e32 v49, v49
	s_nop 0
	v_fmac_f32_e32 v81, v51, v49
